# adds spatial-gating epilogue change: the two per-row bias loads issued at unit start instead of right before use (two exposed load latencies per unit removed)
# speedup vs baseline: 1.0055x; 1.0055x over previous
.LBB0_480:
	s_lshr_b32 s34, s6, 3
	s_lshl_b64 s[14:15], s[34:35], 7
	s_and_b32 s13, s6, 7
	v_mov_b32_e32 v1, s15
	v_or_b32_e32 v0, s14, v82
	s_lshl_b32 s34, s13, 8
	v_lshl_add_u64 v[4:5], v[0:1], 0, s[44:45]
	v_lshl_add_u64 v[0:1], v[0:1], 0, s[48:49]
	v_lshl_add_u64 v[2:3], v[42:43], 0, s[34:35]
	v_lshlrev_b64 v[4:5], 12, v[4:5]
	v_lshlrev_b64 v[0:1], 12, v[0:1]
	v_lshl_add_u64 v[4:5], v[2:3], 0, v[4:5]
	v_lshl_add_u64 v[0:1], v[2:3], 0, v[0:1]
	s_lshl_b32 s98, s13, 7
	s_mov_b32 s99, 0
	v_add_lshl_u32 v136, v50, s98, 2
	v_lshl_add_u64 v[134:135], v[60:61], 0, s[98:99]
	global_load_dword v150, v136, s[10:11]
	v_lshl_add_u64 v[134:135], v[134:135], 2, s[10:11]
	global_load_dword v151, v[134:135], off offset:384
	global_load_dwordx2 v[76:77], v[4:5], off
	global_load_dwordx2 v[74:75], v[4:5], off offset:16
	global_load_dwordx2 v[72:73], v[4:5], off offset:32
	global_load_dwordx2 v[70:71], v[4:5], off offset:48
	global_load_dwordx2 v[68:69], v[0:1], off
	global_load_dwordx2 v[66:67], v[0:1], off offset:16
	global_load_dwordx2 v[64:65], v[0:1], off offset:32
	global_load_dwordx2 v[62:63], v[0:1], off offset:48
	s_waitcnt lgkmcnt(0)
	s_barrier
	s_lshl_b32 s16, s13, 7
	s_cmp_eq_u32 s13, s29
	s_cbranch_scc1 .LBB0_484
	s_and_saveexec_b64 s[6:7], s[0:1]
	s_cbranch_execz .LBB0_483
	v_add_u32_e32 v0, s16, v240
	v_ashrrev_i32_e32 v1, 31, v0
	v_lshl_add_u64 v[2:3], v[0:1], 2, s[2:3]
	v_mov_b32_e32 v1, v81
	s_movk_i32 s38, 0xfe00
	v_lshl_add_u64 v[0:1], v[0:1], 2, s[8:9]
	s_mov_b32 s39, -1
	v_lshl_add_u64 v[0:1], v[0:1], 0, s[38:39]
	v_cndmask_b32_e64 v1, v1, v3, s[4:5]
	v_cndmask_b32_e64 v0, v0, v2, s[4:5]
	global_load_dword v0, v[0:1], off
	s_waitcnt vmcnt(0)
	ds_write_b32 v33, v0

.LBB0_486:
	s_waitcnt lgkmcnt(0)
	s_barrier
	ds_read_b128 v[0:3], v119
	ds_read_b128 v[122:125], v119 offset:32
	ds_read_b128 v[4:7], v120
	ds_read_b128 v[126:129], v120 offset:32
	v_add_lshl_u32 v80, v50, s16, 2
	s_waitcnt lgkmcnt(1)
	v_mfma_f32_32x32x16_bf16 v[16:31], v[0:3], v[4:7], 0
	ds_read_b128 v[4:7], v121
	ds_read_b128 v[130:133], v121 offset:32
	s_or_b32 s6, s16, s31
	v_lshl_add_u64 v[78:79], s[14:15], 0, v[50:51]
	s_lshr_b32 s6, s6, 6
	s_or_b32 s6, s6, 16
	v_readlane_b32 s38, v253, 57
	v_readlane_b32 s39, v253, 58
	s_waitcnt lgkmcnt(1)
	v_mfma_f32_32x32x16_bf16 v[0:15], v[0:3], v[4:7], 0
	s_mov_b32 s17, s35
	v_mfma_f32_32x32x16_bf16 v[16:31], v[122:125], v[126:129], v[16:31]
	s_waitcnt lgkmcnt(0)
	v_mfma_f32_32x32x16_bf16 v[0:15], v[122:125], v[130:133], v[0:15]
	ds_read_b128 v[122:125], v119 offset:64
	ds_read_b128 v[126:129], v120 offset:64
	s_waitcnt lgkmcnt(0)
	v_mfma_f32_32x32x16_bf16 v[16:31], v[122:125], v[126:129], v[16:31]
	ds_read_b128 v[126:129], v121 offset:64
	s_waitcnt lgkmcnt(0)
	v_mfma_f32_32x32x16_bf16 v[0:15], v[122:125], v[126:129], v[0:15]
	ds_read_b128 v[122:125], v119 offset:96
	ds_read_b128 v[126:129], v120 offset:96
	s_waitcnt lgkmcnt(0)
	v_mfma_f32_32x32x16_bf16 v[16:31], v[122:125], v[126:129], v[16:31]
	ds_read_b128 v[126:129], v121 offset:96
	s_waitcnt lgkmcnt(0)
	v_mfma_f32_32x32x16_bf16 v[0:15], v[122:125], v[126:129], v[0:15]
	ds_read_b128 v[122:125], v119 offset:128
	ds_read_b128 v[126:129], v121 offset:128
	s_waitcnt lgkmcnt(0)
	v_mfma_f32_32x32x16_bf16 v[0:15], v[122:125], v[126:129], v[0:15]
	ds_read_b128 v[122:125], v119 offset:160
	ds_read_b128 v[126:129], v121 offset:160
	s_waitcnt lgkmcnt(0)
	v_mfma_f32_32x32x16_bf16 v[0:15], v[122:125], v[126:129], v[0:15]
	ds_read_b128 v[122:125], v119 offset:192
	ds_read_b128 v[126:129], v121 offset:192
	s_waitcnt lgkmcnt(0)
	v_mfma_f32_32x32x16_bf16 v[0:15], v[122:125], v[126:129], v[0:15]
	ds_read_b128 v[122:125], v119 offset:224
	ds_read_b128 v[126:129], v121 offset:224
	s_waitcnt lgkmcnt(0)
	v_mfma_f32_32x32x16_bf16 v[0:15], v[122:125], v[126:129], v[0:15]
	v_lshrrev_b64 v[122:123], 2, v[78:79]
	v_lshlrev_b32_e32 v80, 6, v78
	v_and_b32_e32 v79, 0xffffffe0, v122
	v_and_or_b32 v125, v80, s43, v137
	s_waitcnt vmcnt(7)
	v_lshlrev_b32_e32 v80, 16, v76
	v_and_b32_e32 v76, 0xffff0000, v76
	v_or_b32_e32 v122, s6, v79
	v_lshrrev_b32_e32 v79, 3, v78
	v_and_or_b32 v79, v79, 14, s42
	v_lshlrev_b32_e32 v78, 2, v78
	v_lshlrev_b32_e32 v126, 10, v79
	v_and_b32_e32 v127, 32, v78
	v_lshlrev_b64 v[78:79], 14, v[122:123]
	v_lshl_add_u64 v[78:79], s[38:39], 0, v[78:79]
	s_waitcnt vmcnt(0)
	v_add_f32_e32 v16, v150, v16
	v_add_f32_e32 v17, v150, v17
	v_mul_f32_e32 v16, v16, v80
	v_mul_f32_e32 v17, v17, v76
	v_cvt_pk_bf16_f32 v16, v16, v17
	v_lshlrev_b32_e32 v17, 16, v77
	v_add_f32_e32 v18, v150, v18
	v_mul_f32_e32 v17, v18, v17
	v_and_b32_e32 v18, 0xffff0000, v77
	v_add_f32_e32 v19, v150, v19
	v_mul_f32_e32 v18, v19, v18
	v_or3_b32 v80, v125, v127, v126
	v_cvt_pk_bf16_f32 v17, v17, v18
	v_lshl_add_u64 v[18:19], v[78:79], 0, v[80:81]
	global_store_dwordx2 v[18:19], v[16:17], off
	v_lshlrev_b32_e32 v16, 16, v74
	v_add_f32_e32 v17, v150, v20
	v_mul_f32_e32 v16, v17, v16
	v_and_b32_e32 v17, 0xffff0000, v74
	v_add_f32_e32 v18, v150, v21
	v_mul_f32_e32 v17, v18, v17
	v_cvt_pk_bf16_f32 v16, v16, v17
	v_lshlrev_b32_e32 v17, 16, v75
	v_add_f32_e32 v18, v150, v22
	v_mul_f32_e32 v17, v18, v17
	v_and_b32_e32 v18, 0xffff0000, v75
	v_add_f32_e32 v19, v150, v23
	v_mul_f32_e32 v18, v19, v18
	v_or_b32_e32 v80, 16, v80
	v_cvt_pk_bf16_f32 v17, v17, v18
	v_lshl_add_u64 v[18:19], v[78:79], 0, v[80:81]
	global_store_dwordx2 v[18:19], v[16:17], off
	v_lshlrev_b32_e32 v16, 16, v72
	v_add_f32_e32 v17, v150, v24
	v_mul_f32_e32 v16, v17, v16
	v_and_b32_e32 v17, 0xffff0000, v72
	v_add_f32_e32 v18, v150, v25
	v_mul_f32_e32 v17, v18, v17
	v_cvt_pk_bf16_f32 v16, v16, v17
	v_lshlrev_b32_e32 v17, 16, v73
	v_add_f32_e32 v18, v150, v26
	v_mul_f32_e32 v17, v18, v17
	v_and_b32_e32 v18, 0xffff0000, v73
	v_add_f32_e32 v19, v150, v27
	v_mul_f32_e32 v18, v19, v18
	v_cvt_pk_bf16_f32 v17, v17, v18
	v_or_b32_e32 v18, 32, v125
	v_bitop3_b32 v80, v18, v126, v127 bitop3:0xde
	v_lshl_add_u64 v[18:19], v[78:79], 0, v[80:81]
	global_store_dwordx2 v[18:19], v[16:17], off
	v_lshlrev_b32_e32 v16, 16, v70
	v_add_f32_e32 v17, v150, v28
	v_mul_f32_e32 v16, v17, v16
	v_and_b32_e32 v17, 0xffff0000, v70
	v_add_f32_e32 v18, v150, v29
	v_mul_f32_e32 v17, v18, v17
	v_cvt_pk_bf16_f32 v16, v16, v17
	v_lshlrev_b32_e32 v17, 16, v71
	v_add_f32_e32 v18, v150, v30
	v_mul_f32_e32 v17, v18, v17
	v_and_b32_e32 v18, 0xffff0000, v71
	v_add_f32_e32 v19, v150, v31
	v_mul_f32_e32 v18, v19, v18
	v_cvt_pk_bf16_f32 v17, v17, v18
	v_or_b32_e32 v18, 48, v125
	v_bitop3_b32 v80, v18, v126, v127 bitop3:0xde
	v_lshl_add_u64 v[18:19], v[78:79], 0, v[80:81]
	global_store_dwordx2 v[18:19], v[16:17], off
	v_lshl_add_u64 v[16:17], s[14:15], 0, v[48:49]
	v_lshrrev_b64 v[18:19], 2, v[16:17]
	v_and_b32_e32 v17, 0xffffffe0, v18
	v_or_b32_e32 v18, s6, v17
	v_lshrrev_b32_e32 v17, 3, v16
	v_and_b32_e32 v19, 0x3ffff, v19
	v_and_or_b32 v17, v17, 14, s42
	v_lshlrev_b32_e32 v21, 6, v16
	v_lshlrev_b32_e32 v16, 2, v16
	v_lshlrev_b32_e32 v22, 10, v17
	v_and_b32_e32 v23, 32, v16
	v_lshlrev_b64 v[16:17], 14, v[18:19]
	v_lshlrev_b32_e32 v18, 16, v68
	v_and_or_b32 v21, v21, s43, v137
	v_lshl_add_u64 v[16:17], s[38:39], 0, v[16:17]
	v_or3_b32 v80, v21, v23, v22
	v_readlane_b32 s6, v254, 23
	v_readlane_b32 s7, v254, 24
	s_and_b64 vcc, exec, s[6:7]
	s_mov_b32 s6, s18
	s_nop 0
	v_add_f32_e32 v0, v151, v0
	v_mul_f32_e32 v0, v0, v18
	v_and_b32_e32 v18, 0xffff0000, v68
	v_add_f32_e32 v1, v151, v1
	v_mul_f32_e32 v1, v1, v18
	v_cvt_pk_bf16_f32 v0, v0, v1
	v_lshlrev_b32_e32 v1, 16, v69
	v_add_f32_e32 v2, v151, v2
	v_mul_f32_e32 v1, v2, v1
	v_and_b32_e32 v2, 0xffff0000, v69
	v_add_f32_e32 v3, v151, v3
	v_mul_f32_e32 v2, v3, v2
	v_cvt_pk_bf16_f32 v1, v1, v2
	v_lshl_add_u64 v[2:3], v[16:17], 0, v[80:81]
	global_store_dwordx2 v[2:3], v[0:1], off
	v_lshlrev_b32_e32 v0, 16, v66
	v_add_f32_e32 v1, v151, v4
	v_mul_f32_e32 v0, v1, v0
	v_and_b32_e32 v1, 0xffff0000, v66
	v_add_f32_e32 v2, v151, v5
	v_mul_f32_e32 v1, v2, v1
	v_cvt_pk_bf16_f32 v0, v0, v1
	v_lshlrev_b32_e32 v1, 16, v67
	v_add_f32_e32 v2, v151, v6
	v_mul_f32_e32 v1, v2, v1
	v_and_b32_e32 v2, 0xffff0000, v67
	v_add_f32_e32 v3, v151, v7
	v_mul_f32_e32 v2, v3, v2
	v_or_b32_e32 v80, 16, v80
	v_cvt_pk_bf16_f32 v1, v1, v2
	v_lshl_add_u64 v[2:3], v[16:17], 0, v[80:81]
	global_store_dwordx2 v[2:3], v[0:1], off
	v_lshlrev_b32_e32 v0, 16, v64
	v_add_f32_e32 v1, v151, v8
	v_mul_f32_e32 v0, v1, v0
	v_and_b32_e32 v1, 0xffff0000, v64
	v_add_f32_e32 v2, v151, v9
	v_mul_f32_e32 v1, v2, v1
	v_cvt_pk_bf16_f32 v0, v0, v1
	v_lshlrev_b32_e32 v1, 16, v65
	v_add_f32_e32 v2, v151, v10
	v_mul_f32_e32 v1, v2, v1
	v_and_b32_e32 v2, 0xffff0000, v65
	v_add_f32_e32 v3, v151, v11
	v_mul_f32_e32 v2, v3, v2
	v_cvt_pk_bf16_f32 v1, v1, v2
	v_or_b32_e32 v2, 32, v21
	v_bitop3_b32 v80, v2, v22, v23 bitop3:0xde
	v_lshl_add_u64 v[2:3], v[16:17], 0, v[80:81]
	global_store_dwordx2 v[2:3], v[0:1], off
	v_lshlrev_b32_e32 v0, 16, v62
	v_add_f32_e32 v1, v151, v12
	v_mul_f32_e32 v0, v1, v0
	v_and_b32_e32 v1, 0xffff0000, v62
	v_add_f32_e32 v2, v151, v13
	v_mul_f32_e32 v1, v2, v1
	v_cvt_pk_bf16_f32 v0, v0, v1
	v_lshlrev_b32_e32 v1, 16, v63
	v_add_f32_e32 v2, v151, v14
	v_mul_f32_e32 v1, v2, v1
	v_and_b32_e32 v2, 0xffff0000, v63
	v_add_f32_e32 v3, v151, v15
	v_mul_f32_e32 v2, v3, v2
	v_cvt_pk_bf16_f32 v1, v1, v2
	v_or_b32_e32 v2, 48, v21
	v_bitop3_b32 v80, v2, v22, v23 bitop3:0xde
	v_lshl_add_u64 v[2:3], v[16:17], 0, v[80:81]
	global_store_dwordx2 v[2:3], v[0:1], off
	s_cbranch_vccnz .LBB0_488
	v_readlane_b32 s6, v250, 4
	s_add_i32 s6, s28, s6
